# v27 plus: SwiGLU hidden tensor stored K-tile-major (32 KB contiguous blocks per 256-row panel and 64-wide K-tile) so the FFN-down GEMM's A-operand DMA reads are contiguous
# speedup vs baseline: 1.0121x; 1.0003x over previous
.LBB0_455:
	s_cmp_gt_i32 s81, 1
	v_writelane_b32 v255, s4, 49
	s_cselect_b64 s[0:1], -1, 0
	s_cmp_lt_i32 s80, 2
	v_writelane_b32 v255, s5, 50
	s_cselect_b32 s4, 7, 5
	s_cmp_lt_i32 s81, s4
	v_writelane_b32 v255, s3, 51
	s_cselect_b64 s[2:3], -1, 0
	s_and_b64 s[6:7], s[2:3], exec
	s_cselect_b32 s5, 1, 2
	s_and_b64 s[0:1], s[0:1], s[2:3]
	s_and_b64 vcc, s[0:1], exec
	s_cselect_b32 s6, 3, 5
	s_cmp_gt_i32 s81, 1
	v_cndmask_b32_e64 v209, 0.5, 1.0, s[0:1]
	s_cselect_b64 s[0:1], -1, 0
	s_and_b64 s[2:3], s[0:1], exec
	s_cselect_b32 s5, s5, 0
	s_cselect_b32 s2, s6, 1
	s_add_u32 s46, s60, 0x100000
	s_addc_u32 s47, s61, 0
	s_add_u32 s44, s60, 0xa000000
	s_addc_u32 s45, s61, 0
	s_add_u32 s48, s60, 0x12000000
	s_addc_u32 s49, s61, 0
	s_cmp_gt_i32 s80, 1
	s_mul_i32 s3, s80, 6
	s_cselect_b64 s[12:13], -1, 0
	s_add_i32 s2, s2, s3
	s_lshl_b32 s2, s2, 10
	s_ashr_i32 s3, s2, 31
	s_lshl_b64 s[2:3], s[2:3], 2
	s_add_u32 s2, s60, s2
	s_addc_u32 s3, s61, s3
	s_add_u32 s68, s2, 0x3d000000
	s_addc_u32 s69, s3, 0
	s_cmp_eq_u32 s80, 3
	s_cselect_b64 s[2:3], -1, 0
	s_cmp_eq_u32 s5, 2
	s_cselect_b64 s[6:7], -1, 0
	s_and_b64 s[2:3], s[2:3], s[6:7]
	v_readlane_b32 s8, v254, 0
	s_and_b64 s[2:3], s[2:3], exec
	v_readlane_b32 s10, v254, 2
	v_readlane_b32 s11, v254, 3
	s_mov_b64 s[2:3], s[10:11]
	s_cselect_b32 s39, s3, 0
	s_cselect_b32 s38, s2, 0
	s_add_u32 s76, s60, 0x9e00000
	s_mul_i32 s2, s80, 3
	s_addc_u32 s77, s61, 0
	s_add_i32 s5, s5, s2
	s_lshl_b32 s2, s5, 5
	s_add_i32 s84, s2, 32
	s_mov_b64 s[2:3], -1
	v_readlane_b32 s9, v254, 1
	s_cbranch_vccnz .LBB0_582
	v_cndmask_b32_e64 v0, 0, 1, s[0:1]
	s_and_b64 s[0:1], s[0:1], exec
	s_cselect_b32 s0, s4, 0
	s_lshl_b32 s1, s80, 1
	v_readfirstlane_b32 s2, v0
	s_or_b32 s1, s1, s2
	s_mul_hi_i32 s2, s1, 0x1080000
	s_mul_i32 s1, s1, 0x1080000
	s_add_u32 s1, s60, s1
	s_addc_u32 s2, s61, s2
	s_add_u32 s30, s1, 0x200000
	s_addc_u32 s31, s2, 0
	s_cmp_lg_u32 s81, s0
	s_mov_b64 s[0:1], -1
	s_cbranch_scc0 .LBB0_560
	v_readlane_b32 s0, v254, 9
	s_waitcnt vmcnt(0)
	v_mov_b32_e32 v12, v200
	v_readlane_b32 s1, v254, 10
	s_andn2_b64 vcc, exec, s[0:1]
	v_readfirstlane_b32 s1, v12
	s_cbranch_vccnz .LBB0_559
	s_mov_b64 s[98:99], 0x8000
	v_lshlrev_b32_e32 v0, 4, v12
	s_waitcnt lgkmcnt(0)
	v_add_u32_e32 v1, 0x2000, v0
	v_ashrrev_i32_e32 v2, 31, v1
	v_lshrrev_b32_e32 v2, 22, v2
	v_add_u32_e32 v2, v1, v2
	v_ashrrev_i32_e32 v8, 10, v2
	v_mul_i32_i24_e32 v2, 0x400, v8
	v_sub_u32_e32 v1, v1, v2
	v_lshrrev_b32_e32 v2, 4, v1
	v_bitop3_b32 v1, v2, v1, 32 bitop3:0x6c
	v_ashrrev_i32_e32 v2, 31, v1
	v_lshrrev_b32_e32 v2, 26, v2
	v_add_u32_e32 v2, v1, v2
	v_lshlrev_b32_e32 v3, 3, v8
	v_ashrrev_i32_e32 v9, 6, v2
	v_and_b32_e32 v3, -16, v3
	v_add_u32_e32 v3, v9, v3
	v_and_b32_e32 v4, 3, v9
	s_mov_b32 s3, 0xffffe0
	v_lshrrev_b32_e32 v5, 2, v3
	v_lshlrev_b32_e32 v6, 1, v3
	v_and_b32_e32 v2, 0xc0, v2
	v_and_or_b32 v4, v3, s3, v4
	v_and_b32_e32 v5, 4, v5
	v_and_b32_e32 v6, 24, v6
	v_sub_u32_e32 v1, v1, v2
	v_or3_b32 v4, v4, v5, v6
	v_lshlrev_b32_e32 v5, 5, v8
	v_ashrrev_i16_sdwa v1, v207, sext(v1) dst_sel:DWORD dst_unused:UNUSED_PAD src0_sel:DWORD src1_sel:BYTE_0
	v_and_b32_e32 v10, 32, v5
	v_bfe_i32 v11, v1, 0, 16
	s_movk_i32 s4, 0xb00
	v_mul_u32_u24_e32 v4, 0xb00, v4
	v_add_u32_e32 v1, v10, v11
	v_lshlrev_b32_e32 v2, 6, v3
	v_add_lshl_u32 v182, v4, v1, 1
	v_add_lshl_u32 v184, v1, v2, 1
	v_bfe_i32 v1, v12, 27, 1
	v_lshrrev_b32_e32 v1, 22, v1
	v_add_u32_e32 v1, v0, v1
	v_and_b32_e32 v1, 0xfffffc00, v1
	v_sub_u32_e32 v0, v0, v1
	v_lshrrev_b32_e32 v1, 4, v0
	v_ashrrev_i32_e32 v2, 31, v12
	v_bitop3_b32 v0, v1, v0, 32 bitop3:0x6c
	v_lshrrev_b32_e32 v2, 26, v2
	v_ashrrev_i32_e32 v1, 31, v0
	v_add_u32_e32 v2, v12, v2
	v_lshrrev_b32_e32 v1, 26, v1
	s_waitcnt vmcnt(4)
	v_ashrrev_i32_e32 v14, 6, v2
	v_add_u32_e32 v1, v0, v1
	v_lshlrev_b32_e32 v2, 3, v14
	v_ashrrev_i32_e32 v13, 6, v1
	v_and_b32_e32 v2, -16, v2
	v_add_u32_e32 v2, v13, v2
	s_add_u32 s34, s30, 0xb00000
	v_and_b32_e32 v3, 3, v13
	v_lshrrev_b32_e32 v4, 2, v2
	v_lshlrev_b32_e32 v5, 1, v2
	v_and_b32_e32 v1, 0xc0, v1
	s_addc_u32 s35, s31, 0
	s_ashr_i32 s2, s1, 6
	v_and_or_b32 v3, v2, s3, v3
	v_and_b32_e32 v4, 4, v4
	v_and_b32_e32 v5, 24, v5
	v_sub_u32_e32 v0, v0, v1
	v_lshlrev_b32_e32 v1, 6, v2
	v_readlane_b32 s4, v255, 5
	s_ashr_i32 s0, s1, 8
	s_lshl_b32 s36, s2, 10
	v_or3_b32 v3, v3, v4, v5
	v_lshlrev_b32_e32 v4, 5, v14
	v_ashrrev_i16_sdwa v0, v207, sext(v0) dst_sel:DWORD dst_unused:UNUSED_PAD src0_sel:DWORD src1_sel:BYTE_0
	s_mul_i32 s3, s4, 0x160000
	v_and_b32_e32 v15, 32, v4
	v_bfe_i32 v16, v0, 0, 16
	s_add_u32 s26, s34, s3
	s_mul_hi_i32 s3, s4, 0x160000
	v_mul_u32_u24_e32 v3, 0xb00, v3
	v_add_u32_e32 v0, v15, v16
	s_addc_u32 s27, s35, s3
	s_add_i32 s37, s36, 0
	v_add_lshl_u32 v176, v3, v0, 1
	s_add_i32 m0, s37, 0x10000
	v_add_lshl_u32 v186, v0, v1, 1
	global_load_lds_dwordx4 v176, s[26:27]
	s_add_i32 m0, s37, 0x12000
	s_add_u32 s4, s26, 0xb0000
	global_load_lds_dwordx4 v182, s[26:27]
	s_addc_u32 s5, s27, 0
	s_add_i32 m0, s37, 0x14000
	v_mov_b32_e32 v183, v177
	global_load_lds_dwordx4 v176, s[4:5]
	s_add_i32 m0, s37, 0x16000
	v_mov_b32_e32 v187, v177
	global_load_lds_dwordx4 v182, s[4:5]
	v_readlane_b32 s4, v255, 10
	s_cmpk_eq_i32 s58, 0x100
	s_cselect_b32 s3, 24, 0
	s_add_i32 s4, s4, s3
	s_mul_i32 s3, s4, 0x160000
	s_add_u32 s10, s48, s3
	s_mul_hi_i32 s3, s4, 0x160000
	s_addc_u32 s11, s49, s3
	s_add_i32 s42, s37, 0x2000
	v_readlane_b32 s5, v255, 11
	s_mov_b32 m0, s37
	s_add_u32 s4, s10, 0x4000
	global_load_lds_dwordx4 v186, s[10:11]
	s_mov_b32 m0, s42
	s_addc_u32 s5, s11, 0
	s_add_i32 s43, s37, 0x4000
	global_load_lds_dwordx4 v184, s[10:11]
	s_mov_b32 m0, s43
	s_add_i32 s50, s37, 0x6000
	global_load_lds_dwordx4 v186, s[4:5]
	s_mov_b32 m0, s50
	v_mov_b32_e32 v185, v177
	global_load_lds_dwordx4 v184, s[4:5]
	s_cmp_eq_u32 s0, 1
	v_lshl_add_u64 v[6:7], s[26:27], 0, v[176:177]
	v_lshl_add_u64 v[4:5], s[26:27], 0, v[182:183]
	v_lshl_add_u64 v[0:1], s[10:11], 0, v[186:187]
	s_cselect_b64 s[14:15], -1, 0
	s_cmp_lg_u32 s0, 1
	v_lshl_add_u64 v[2:3], s[10:11], 0, v[184:185]
	s_cbranch_scc1 .LBB0_460
	s_barrier
.LBB0_460:
	s_waitcnt vmcnt(0)
	v_and_b32_e32 v18, 15, v12
	v_bfe_u32 v17, v12, 4, 2
	v_lshl_or_b32 v210, s0, 6, v18
	v_lshlrev_b32_e32 v20, 4, v17
	v_lshlrev_b32_e32 v21, 2, v210
	s_and_b32 s8, s2, 3
	v_lshl_or_b32 v20, v18, 6, v20
	s_lshl_b32 s2, s0, 13
	v_and_b32_e32 v22, 32, v21
	v_lshlrev_b32_e32 v23, 2, v12
	s_add_i32 m0, s37, 0x18000
	v_lshl_add_u64 v[6:7], v[6:7], 0, s[72:73]
	v_bitop3_b32 v22, v20, s2, v22 bitop3:0xde
	s_lshl_b32 s2, s8, 12
	v_and_b32_e32 v23, 32, v23
	s_waitcnt vmcnt(2)
	s_barrier
	global_load_lds_dwordx4 v[6:7], off
	v_lshl_add_u64 v[4:5], v[4:5], 0, s[72:73]
	s_add_i32 m0, s37, 0x1a000
	s_add_i32 s51, s37, 0x8000
	s_add_i32 s54, s37, 0xa000
	v_bitop3_b32 v211, v20, s2, v23 bitop3:0xde
	global_load_lds_dwordx4 v[4:5], off
	v_lshl_add_u64 v[0:1], v[0:1], 0, s[98:99]
	s_mov_b32 m0, s51
	s_add_u32 s2, s26, 0xb0080
	global_load_lds_dwordx4 v[0:1], off
	v_lshl_add_u64 v[0:1], v[2:3], 0, s[98:99]
	s_mov_b32 m0, s54
	s_addc_u32 s3, s27, 0
	global_load_lds_dwordx4 v[0:1], off
	s_add_i32 m0, s37, 0x1c000
	v_lshl_add_u64 v[0:1], s[2:3], 0, v[176:177]
	global_load_lds_dwordx4 v[0:1], off
	v_lshl_add_u64 v[0:1], s[2:3], 0, v[182:183]
	s_add_i32 m0, s37, 0x1e000
	s_cmpk_lt_u32 s1, 0x100
	global_load_lds_dwordx4 v[0:1], off
	s_cselect_b64 s[16:17], -1, 0
	s_lshl_b32 s1, s0, 2
	s_or_b32 s1, s1, s8
	v_and_b32_e32 v0, 63, v12
	v_and_b32_e32 v1, 31, v12
	v_lshl_or_b32 v213, s1, 5, v1
	v_lshl_or_b32 v214, s1, 6, v0
	s_movk_i32 s1, 0x100
	v_cmp_gt_i32_e64 s[6:7], s1, v214
	s_lshl_b32 s1, s8, 2
	s_add_i32 s1, s1, 0
	s_lshl_b32 s0, s0, 10
	s_add_i32 s9, s1, 0x20400
	s_add_i32 s20, s9, s0
	s_lshl_b32 s0, s8, 7
	v_readlane_b32 s1, v255, 37
	v_lshlrev_b32_e32 v19, 3, v17
	s_add_i32 s1, s1, s0
	s_add_i32 s0, s0, 0
	v_lshl_or_b32 v212, s8, 5, v19
	v_lshlrev_b32_e32 v0, 5, v17
	s_add_i32 s0, s0, 0x21c00
	s_movk_i32 s8, 0xb00
	v_add_u32_e32 v222, s1, v0
	v_add_u32_e32 v223, s0, v0
	v_lshrrev_b32_e32 v1, 1, v8
	v_mul_lo_u32 v0, v9, s8
	s_mov_b32 s21, 0xb000
	v_mad_u64_u32 v[0:1], s[0:1], v1, s21, v[0:1]
	v_or_b32_e32 v0, v0, v10
	v_add_lshl_u32 v0, v0, v11, 1
	v_mov_b32_e32 v1, v177
	s_mov_b64 s[22:23], 0xb0080
	v_add_u32_e32 v188, 0xc000, v184
	v_mov_b32_e32 v189, v177
	v_lshrrev_b32_e32 v1, 1, v14
	v_mul_lo_u32 v0, v13, s8
	v_mad_u64_u32 v[0:1], s[0:1], v1, s21, v[0:1]
	s_waitcnt vmcnt(6)
	v_lshlrev_b32_e32 v2, 4, v18
	v_add_u32_e32 v215, 0x80, v210
	v_or_b32_e32 v216, 16, v210
	v_or_b32_e32 v217, 32, v210
	v_or_b32_e32 v218, 48, v210
	v_add_u32_e32 v219, 0x90, v210
	v_add_u32_e32 v220, 0xa0, v210
	v_add_u32_e32 v221, 0xb0, v210
	v_or_b32_e32 v0, v0, v15
	v_readlane_b32 s0, v255, 5
	v_lshlrev_b32_e32 v3, 4, v213
	v_lshlrev_b32_e32 v4, 4, v210
	v_lshlrev_b32_e32 v5, 4, v216
	v_lshlrev_b32_e32 v6, 4, v217
	v_lshlrev_b32_e32 v7, 4, v218
	v_lshlrev_b32_e32 v12, 4, v215
	v_lshlrev_b32_e32 v18, 4, v219
	v_lshlrev_b32_e32 v19, 4, v220
	v_lshlrev_b32_e32 v20, 4, v221
	s_cmp_lg_u64 s[38:39], 0
	v_add_lshl_u32 v0, v0, v16, 1
	v_mov_b32_e32 v1, v177
	v_add_u32_e32 v234, s20, v2
	s_mov_b32 s20, s0
	v_readlane_b32 s0, v255, 10
	s_mov_b32 s55, 0
	v_cmp_eq_u32_e64 s[2:3], 0, v17
	v_cmp_gt_u32_e64 s[4:5], 2, v17
	v_add_u32_e32 v224, s63, v21
	s_cselect_b64 s[18:19], -1, 0
	v_add_u32_e32 v190, 0xc000, v186
	v_mov_b32_e32 v191, v177
	s_mov_b32 s56, -1
	v_add_u32_e32 v225, 0, v22
	v_add_u32_e32 v226, s9, v4
	v_add_u32_e32 v227, s9, v5
	v_add_u32_e32 v228, s9, v6
	v_add_u32_e32 v229, s9, v7
	v_add_u32_e32 v230, s9, v12
	v_add_u32_e32 v231, s9, v18
	v_add_u32_e32 v232, s9, v19
	v_add_u32_e32 v233, s9, v20
	v_add_u32_e32 v235, 0, v3
	s_cmpk_eq_i32 s58, 0x100
	s_cselect_b32 s21, 24, 0
	s_add_i32 s21, s21, s0
	s_barrier
	v_readlane_b32 s1, v255, 11
	s_branch .LBB0_463

.LBB0_473:
	s_add_u32 s71, s26, 0x100
	s_addc_u32 s78, s27, 0
	s_mov_b32 s53, -2
	s_waitcnt lgkmcnt(0)
	s_add_u32 s0, s10, 0x10000
	s_addc_u32 s1, s11, 0
	s_add_i32 s79, 0, 0x10000
	s_cmp_eq_u32 s53, 40
	s_cselect_b32 s29, s23, s1
	s_cselect_b32 s28, s22, s0
	s_cselect_b32 s27, s25, s78
	s_cselect_b32 s26, s24, s71
	s_add_i32 s85, 0, 0x14000
	v_add_u32_e32 v128, s79, v211
	v_add_u32_e32 v156, s85, v211
	ds_read_b128 v[112:115], v128
	ds_read_b128 v[116:119], v128 offset:1024
	ds_read_b128 v[124:127], v128 offset:2048
	ds_read_b128 v[128:131], v128 offset:3072
	ds_read_b128 v[144:147], v156
	ds_read_b128 v[148:151], v156 offset:1024
	ds_read_b128 v[152:155], v156 offset:2048
	ds_read_b128 v[156:159], v156 offset:3072
	v_lshl_add_u64 v[244:245], s[10:11], 0, v[190:191]
	s_add_i32 m0, s37, 0xc000
	ds_read_b128 v[160:163], v225
	ds_read_b128 v[164:167], v225 offset:1024
	ds_read_b128 v[168:171], v225 offset:2048
	ds_read_b128 v[172:175], v225 offset:3072
	ds_read_b128 v[192:195], v225 offset:4096
	ds_read_b128 v[196:199], v225 offset:5120
	ds_read_b128 v[236:239], v225 offset:6144
	ds_read_b128 v[240:243], v225 offset:7168
	global_load_lds_dwordx4 v[244:245], off
	v_lshl_add_u64 v[244:245], s[10:11], 0, v[188:189]
	s_add_i32 m0, s37, 0xe000
	s_nop 0
	global_load_lds_dwordx4 v[244:245], off
	s_waitcnt vmcnt(8)
	s_waitcnt lgkmcnt(0)
	s_barrier
	s_setprio 1
	s_waitcnt lgkmcnt(0)
	v_mfma_f32_16x16x32_f16 v[140:143], v[112:115], v[160:163], 0
	v_mfma_f32_16x16x32_f16 v[136:139], v[124:127], v[160:163], 0
	v_mfma_f32_16x16x32_f16 v[108:111], v[112:115], v[168:171], 0
	v_mfma_f32_16x16x32_f16 v[104:107], v[124:127], v[168:171], 0
	v_mfma_f32_16x16x32_f16 v[92:95], v[112:115], v[192:195], 0
	v_mfma_f32_16x16x32_f16 v[88:91], v[124:127], v[192:195], 0
	v_mfma_f32_16x16x32_f16 v[76:79], v[112:115], v[236:239], 0
	v_mfma_f32_16x16x32_f16 v[72:75], v[124:127], v[236:239], 0
	v_mfma_f32_16x16x32_f16 v[140:143], v[116:119], v[164:167], v[140:143]
	v_mfma_f32_16x16x32_f16 v[136:139], v[128:131], v[164:167], v[136:139]
	v_mfma_f32_16x16x32_f16 v[108:111], v[116:119], v[172:175], v[108:111]
	v_mfma_f32_16x16x32_f16 v[104:107], v[128:131], v[172:175], v[104:107]
	v_mfma_f32_16x16x32_f16 v[92:95], v[116:119], v[196:199], v[92:95]
	v_mfma_f32_16x16x32_f16 v[88:91], v[128:131], v[196:199], v[88:91]
	v_mfma_f32_16x16x32_f16 v[76:79], v[116:119], v[240:243], v[76:79]
	v_mfma_f32_16x16x32_f16 v[72:75], v[128:131], v[240:243], v[72:75]
	s_setprio 0
	s_setprio 1
	v_mfma_f32_16x16x32_f16 v[132:135], v[144:147], v[160:163], 0
	v_mfma_f32_16x16x32_f16 v[120:123], v[152:155], v[160:163], 0
	v_mfma_f32_16x16x32_f16 v[100:103], v[144:147], v[168:171], 0
	v_mfma_f32_16x16x32_f16 v[96:99], v[152:155], v[168:171], 0
	v_mfma_f32_16x16x32_f16 v[84:87], v[144:147], v[192:195], 0
	v_mfma_f32_16x16x32_f16 v[80:83], v[152:155], v[192:195], 0
	v_mfma_f32_16x16x32_f16 v[68:71], v[144:147], v[236:239], 0
	v_mfma_f32_16x16x32_f16 v[64:67], v[152:155], v[236:239], 0
	v_mfma_f32_16x16x32_f16 v[132:135], v[148:151], v[164:167], v[132:135]
	v_mfma_f32_16x16x32_f16 v[120:123], v[156:159], v[164:167], v[120:123]
	v_mfma_f32_16x16x32_f16 v[100:103], v[148:151], v[172:175], v[100:103]
	v_mfma_f32_16x16x32_f16 v[96:99], v[156:159], v[172:175], v[96:99]
	v_mfma_f32_16x16x32_f16 v[84:87], v[148:151], v[196:199], v[84:87]
	v_mfma_f32_16x16x32_f16 v[80:83], v[156:159], v[196:199], v[80:83]
	v_mfma_f32_16x16x32_f16 v[68:71], v[148:151], v[240:243], v[68:71]
	v_mfma_f32_16x16x32_f16 v[64:67], v[156:159], v[240:243], v[64:67]
	s_setprio 0
	s_barrier
	s_add_i32 s10, s79, s36
	v_lshl_add_u64 v[244:245], s[26:27], 0, v[176:177]
	s_mov_b32 m0, s10
	ds_read_b128 v[160:163], v225 offset:16384
	ds_read_b128 v[164:167], v225 offset:17408
	ds_read_b128 v[168:171], v225 offset:18432
	ds_read_b128 v[172:175], v225 offset:19456
	ds_read_b128 v[192:195], v225 offset:20480
	ds_read_b128 v[196:199], v225 offset:21504
	ds_read_b128 v[236:239], v225 offset:22528
	ds_read_b128 v[240:243], v225 offset:23552
	global_load_lds_dwordx4 v[244:245], off
	s_add_i32 m0, s10, 0x2000
	s_add_u32 s10, s26, 0xb0000
	v_lshl_add_u64 v[246:247], s[26:27], 0, v[182:183]
	s_addc_u32 s11, s27, 0
	s_add_i32 s79, s85, s36
	global_load_lds_dwordx4 v[246:247], off
	v_lshl_add_u64 v[248:249], s[10:11], 0, v[176:177]
	s_mov_b32 m0, s79
	v_lshl_add_u64 v[250:251], s[28:29], 0, v[184:185]
	global_load_lds_dwordx4 v[248:249], off
	v_lshl_add_u64 v[248:249], s[10:11], 0, v[182:183]
	s_add_i32 m0, s79, 0x2000
	s_nop 0
	global_load_lds_dwordx4 v[248:249], off
	v_lshl_add_u64 v[248:249], s[28:29], 0, v[186:187]
	s_mov_b32 m0, s37
	s_nop 0
	global_load_lds_dwordx4 v[248:249], off
	s_mov_b32 m0, s42
	s_nop 0
	global_load_lds_dwordx4 v[250:251], off
	s_waitcnt vmcnt(8)
	s_waitcnt lgkmcnt(0)
	s_barrier
	s_setprio 1
	s_waitcnt lgkmcnt(0)
	v_mfma_f32_16x16x32_f16 v[60:63], v[112:115], v[160:163], 0
	v_mfma_f32_16x16x32_f16 v[56:59], v[124:127], v[160:163], 0
	v_mfma_f32_16x16x32_f16 v[44:47], v[112:115], v[168:171], 0
	v_mfma_f32_16x16x32_f16 v[40:43], v[124:127], v[168:171], 0
	v_mfma_f32_16x16x32_f16 v[28:31], v[112:115], v[192:195], 0
	v_mfma_f32_16x16x32_f16 v[24:27], v[124:127], v[192:195], 0
	v_mfma_f32_16x16x32_f16 v[12:15], v[112:115], v[236:239], 0
	v_mfma_f32_16x16x32_f16 v[8:11], v[124:127], v[236:239], 0
	v_mfma_f32_16x16x32_f16 v[60:63], v[116:119], v[164:167], v[60:63]
	v_mfma_f32_16x16x32_f16 v[56:59], v[128:131], v[164:167], v[56:59]
	v_mfma_f32_16x16x32_f16 v[44:47], v[116:119], v[172:175], v[44:47]
	v_mfma_f32_16x16x32_f16 v[40:43], v[128:131], v[172:175], v[40:43]
	v_mfma_f32_16x16x32_f16 v[28:31], v[116:119], v[196:199], v[28:31]
	v_mfma_f32_16x16x32_f16 v[24:27], v[128:131], v[196:199], v[24:27]
	v_mfma_f32_16x16x32_f16 v[12:15], v[116:119], v[240:243], v[12:15]
	v_mfma_f32_16x16x32_f16 v[8:11], v[128:131], v[240:243], v[8:11]
	s_setprio 0
	s_setprio 1
	v_mfma_f32_16x16x32_f16 v[52:55], v[144:147], v[160:163], 0
	v_mfma_f32_16x16x32_f16 v[48:51], v[152:155], v[160:163], 0
	v_mfma_f32_16x16x32_f16 v[36:39], v[144:147], v[168:171], 0
	v_mfma_f32_16x16x32_f16 v[32:35], v[152:155], v[168:171], 0
	v_mfma_f32_16x16x32_f16 v[20:23], v[144:147], v[192:195], 0
	v_mfma_f32_16x16x32_f16 v[16:19], v[152:155], v[192:195], 0
	v_mfma_f32_16x16x32_f16 v[4:7], v[144:147], v[236:239], 0
	v_mfma_f32_16x16x32_f16 v[0:3], v[152:155], v[236:239], 0
	v_mfma_f32_16x16x32_f16 v[52:55], v[148:151], v[164:167], v[52:55]
	v_mfma_f32_16x16x32_f16 v[48:51], v[156:159], v[164:167], v[48:51]
	v_mfma_f32_16x16x32_f16 v[36:39], v[148:151], v[172:175], v[36:39]
	v_mfma_f32_16x16x32_f16 v[32:35], v[156:159], v[172:175], v[32:35]
	v_mfma_f32_16x16x32_f16 v[20:23], v[148:151], v[196:199], v[20:23]
	v_mfma_f32_16x16x32_f16 v[16:19], v[156:159], v[196:199], v[16:19]
	v_mfma_f32_16x16x32_f16 v[4:7], v[148:151], v[240:243], v[4:7]
	v_mfma_f32_16x16x32_f16 v[0:3], v[156:159], v[240:243], v[0:3]
	s_setprio 0
	s_barrier
	s_add_i32 s79, 0, 0x18000
	s_add_i32 s85, 0, 0x1c000
	v_add_u32_e32 v128, s79, v211
	v_add_u32_e32 v156, s85, v211
	ds_read_b128 v[112:115], v128
	ds_read_b128 v[116:119], v128 offset:1024
	ds_read_b128 v[124:127], v128 offset:2048
	ds_read_b128 v[128:131], v128 offset:3072
	ds_read_b128 v[144:147], v156
	ds_read_b128 v[148:151], v156 offset:1024
	ds_read_b128 v[152:155], v156 offset:2048
	ds_read_b128 v[156:159], v156 offset:3072
	s_add_u32 s10, s28, 0x4000
	s_addc_u32 s11, s29, 0
	s_mov_b32 m0, s43
	v_lshl_add_u64 v[252:253], s[10:11], 0, v[186:187]
	ds_read_b128 v[160:163], v225 offset:32768
	ds_read_b128 v[164:167], v225 offset:33792
	ds_read_b128 v[168:171], v225 offset:34816
	ds_read_b128 v[172:175], v225 offset:35840
	ds_read_b128 v[192:195], v225 offset:36864
	ds_read_b128 v[196:199], v225 offset:37888
	ds_read_b128 v[236:239], v225 offset:38912
	ds_read_b128 v[240:243], v225 offset:39936
	global_load_lds_dwordx4 v[252:253], off
	v_lshl_add_u64 v[252:253], s[10:11], 0, v[184:185]
	s_mov_b32 m0, s50
	s_nop 0
	global_load_lds_dwordx4 v[252:253], off
	s_waitcnt vmcnt(8)
	s_waitcnt lgkmcnt(0)
	s_barrier
	s_setprio 1
	s_waitcnt lgkmcnt(0)
	v_mfma_f32_16x16x32_f16 v[140:143], v[112:115], v[160:163], v[140:143]
	v_mfma_f32_16x16x32_f16 v[136:139], v[124:127], v[160:163], v[136:139]
	v_mfma_f32_16x16x32_f16 v[108:111], v[112:115], v[168:171], v[108:111]
	v_mfma_f32_16x16x32_f16 v[104:107], v[124:127], v[168:171], v[104:107]
	v_mfma_f32_16x16x32_f16 v[92:95], v[112:115], v[192:195], v[92:95]
	v_mfma_f32_16x16x32_f16 v[88:91], v[124:127], v[192:195], v[88:91]
	v_mfma_f32_16x16x32_f16 v[76:79], v[112:115], v[236:239], v[76:79]
	v_mfma_f32_16x16x32_f16 v[72:75], v[124:127], v[236:239], v[72:75]
	v_mfma_f32_16x16x32_f16 v[140:143], v[116:119], v[164:167], v[140:143]
	v_mfma_f32_16x16x32_f16 v[136:139], v[128:131], v[164:167], v[136:139]
	v_mfma_f32_16x16x32_f16 v[108:111], v[116:119], v[172:175], v[108:111]
	v_mfma_f32_16x16x32_f16 v[104:107], v[128:131], v[172:175], v[104:107]
	v_mfma_f32_16x16x32_f16 v[92:95], v[116:119], v[196:199], v[92:95]
	v_mfma_f32_16x16x32_f16 v[88:91], v[128:131], v[196:199], v[88:91]
	v_mfma_f32_16x16x32_f16 v[76:79], v[116:119], v[240:243], v[76:79]
	v_mfma_f32_16x16x32_f16 v[72:75], v[128:131], v[240:243], v[72:75]
	s_setprio 0
	s_setprio 1
	v_mfma_f32_16x16x32_f16 v[132:135], v[144:147], v[160:163], v[132:135]
	v_mfma_f32_16x16x32_f16 v[120:123], v[152:155], v[160:163], v[120:123]
	v_mfma_f32_16x16x32_f16 v[100:103], v[144:147], v[168:171], v[100:103]
	v_mfma_f32_16x16x32_f16 v[96:99], v[152:155], v[168:171], v[96:99]
	v_mfma_f32_16x16x32_f16 v[84:87], v[144:147], v[192:195], v[84:87]
	v_mfma_f32_16x16x32_f16 v[80:83], v[152:155], v[192:195], v[80:83]
	v_mfma_f32_16x16x32_f16 v[68:71], v[144:147], v[236:239], v[68:71]
	v_mfma_f32_16x16x32_f16 v[64:67], v[152:155], v[236:239], v[64:67]
	v_mfma_f32_16x16x32_f16 v[132:135], v[148:151], v[164:167], v[132:135]
	v_mfma_f32_16x16x32_f16 v[120:123], v[156:159], v[164:167], v[120:123]
	v_mfma_f32_16x16x32_f16 v[100:103], v[148:151], v[172:175], v[100:103]
	v_mfma_f32_16x16x32_f16 v[96:99], v[156:159], v[172:175], v[96:99]
	v_mfma_f32_16x16x32_f16 v[84:87], v[148:151], v[196:199], v[84:87]
	v_mfma_f32_16x16x32_f16 v[80:83], v[156:159], v[196:199], v[80:83]
	v_mfma_f32_16x16x32_f16 v[68:71], v[148:151], v[240:243], v[68:71]
	v_mfma_f32_16x16x32_f16 v[64:67], v[156:159], v[240:243], v[64:67]
	s_setprio 0
	s_barrier
	s_add_i32 s10, s79, s36
	v_lshl_add_u64 v[244:245], v[244:245], 0, s[72:73]
	s_mov_b32 m0, s10
	ds_read_b128 v[160:163], v225 offset:49152
	ds_read_b128 v[164:167], v225 offset:50176
	ds_read_b128 v[168:171], v225 offset:51200
	ds_read_b128 v[172:175], v225 offset:52224
	ds_read_b128 v[192:195], v225 offset:53248
	ds_read_b128 v[196:199], v225 offset:54272
	ds_read_b128 v[236:239], v225 offset:55296
	ds_read_b128 v[240:243], v225 offset:56320
	global_load_lds_dwordx4 v[244:245], off
	s_add_i32 m0, s10, 0x2000
	s_add_u32 s10, s26, 0xb0080
	v_lshl_add_u64 v[244:245], v[246:247], 0, s[72:73]
	s_addc_u32 s11, s27, 0
	s_add_i32 s26, s85, s36
	global_load_lds_dwordx4 v[244:245], off
	v_lshl_add_u64 v[244:245], s[10:11], 0, v[176:177]
	s_mov_b32 m0, s26
	s_nop 0
	global_load_lds_dwordx4 v[244:245], off
	v_lshl_add_u64 v[244:245], s[10:11], 0, v[182:183]
	s_add_i32 m0, s26, 0x2000
	s_nop 0
	global_load_lds_dwordx4 v[244:245], off
	v_lshl_add_u64 v[244:245], v[248:249], 0, s[98:99]
	s_mov_b32 m0, s51
	s_nop 0
	global_load_lds_dwordx4 v[244:245], off
	v_lshl_add_u64 v[244:245], v[250:251], 0, s[98:99]
	s_mov_b32 m0, s54
	s_nop 0
	global_load_lds_dwordx4 v[244:245], off
	s_waitcnt vmcnt(8)
	s_waitcnt lgkmcnt(0)
	s_barrier
	s_setprio 1
	s_waitcnt lgkmcnt(0)
	v_mfma_f32_16x16x32_f16 v[60:63], v[112:115], v[160:163], v[60:63]
	v_mfma_f32_16x16x32_f16 v[56:59], v[124:127], v[160:163], v[56:59]
	v_mfma_f32_16x16x32_f16 v[44:47], v[112:115], v[168:171], v[44:47]
	v_mfma_f32_16x16x32_f16 v[40:43], v[124:127], v[168:171], v[40:43]
	v_mfma_f32_16x16x32_f16 v[28:31], v[112:115], v[192:195], v[28:31]
	v_mfma_f32_16x16x32_f16 v[24:27], v[124:127], v[192:195], v[24:27]
	v_mfma_f32_16x16x32_f16 v[12:15], v[112:115], v[236:239], v[12:15]
	v_mfma_f32_16x16x32_f16 v[8:11], v[124:127], v[236:239], v[8:11]
	v_mfma_f32_16x16x32_f16 v[60:63], v[116:119], v[164:167], v[60:63]
	v_mfma_f32_16x16x32_f16 v[56:59], v[128:131], v[164:167], v[56:59]
	v_mfma_f32_16x16x32_f16 v[44:47], v[116:119], v[172:175], v[44:47]
	v_mfma_f32_16x16x32_f16 v[40:43], v[128:131], v[172:175], v[40:43]
	v_mfma_f32_16x16x32_f16 v[28:31], v[116:119], v[196:199], v[28:31]
	v_mfma_f32_16x16x32_f16 v[24:27], v[128:131], v[196:199], v[24:27]
	v_mfma_f32_16x16x32_f16 v[12:15], v[116:119], v[240:243], v[12:15]
	v_mfma_f32_16x16x32_f16 v[8:11], v[128:131], v[240:243], v[8:11]
	s_setprio 0
	s_setprio 1
	v_mfma_f32_16x16x32_f16 v[52:55], v[144:147], v[160:163], v[52:55]
	v_mfma_f32_16x16x32_f16 v[48:51], v[152:155], v[160:163], v[48:51]
	v_mfma_f32_16x16x32_f16 v[36:39], v[144:147], v[168:171], v[36:39]
	v_mfma_f32_16x16x32_f16 v[32:35], v[152:155], v[168:171], v[32:35]
	v_mfma_f32_16x16x32_f16 v[20:23], v[144:147], v[192:195], v[20:23]
	v_mfma_f32_16x16x32_f16 v[16:19], v[152:155], v[192:195], v[16:19]
	v_mfma_f32_16x16x32_f16 v[4:7], v[144:147], v[236:239], v[4:7]
	v_mfma_f32_16x16x32_f16 v[0:3], v[152:155], v[236:239], v[0:3]
	v_mfma_f32_16x16x32_f16 v[52:55], v[148:151], v[164:167], v[52:55]
	v_mfma_f32_16x16x32_f16 v[48:51], v[156:159], v[164:167], v[48:51]
	v_mfma_f32_16x16x32_f16 v[36:39], v[148:151], v[172:175], v[36:39]
	v_mfma_f32_16x16x32_f16 v[32:35], v[156:159], v[172:175], v[32:35]
	v_mfma_f32_16x16x32_f16 v[20:23], v[148:151], v[196:199], v[20:23]
	v_mfma_f32_16x16x32_f16 v[16:19], v[156:159], v[196:199], v[16:19]
	v_mfma_f32_16x16x32_f16 v[4:7], v[148:151], v[240:243], v[4:7]
	v_mfma_f32_16x16x32_f16 v[0:3], v[156:159], v[240:243], v[0:3]
	s_setprio 0
	s_barrier
	s_add_i32 s53, s53, 2
	s_add_u32 s71, s71, 0x100
	s_addc_u32 s78, s78, 0
	s_cmp_gt_u32 s53, 41
	s_mov_b64 s[10:11], s[0:1]
.LBB0_474:
	s_add_u32 s0, s10, 0x10000
	s_addc_u32 s1, s11, 0
	s_add_i32 s79, 0, 0x10000
	s_cmp_eq_u32 s53, 40
	s_cselect_b32 s29, s23, s1
	s_cselect_b32 s28, s22, s0
	s_cselect_b32 s27, s25, s78
	s_cselect_b32 s26, s24, s71
	s_add_i32 s85, 0, 0x14000
	v_add_u32_e32 v128, s79, v211
	v_add_u32_e32 v156, s85, v211
	ds_read_b128 v[112:115], v128
	ds_read_b128 v[116:119], v128 offset:1024
	ds_read_b128 v[124:127], v128 offset:2048
	ds_read_b128 v[128:131], v128 offset:3072
	ds_read_b128 v[144:147], v156
	ds_read_b128 v[148:151], v156 offset:1024
	ds_read_b128 v[152:155], v156 offset:2048
	ds_read_b128 v[156:159], v156 offset:3072
	v_lshl_add_u64 v[244:245], s[10:11], 0, v[190:191]
	s_add_i32 m0, s37, 0xc000
	ds_read_b128 v[160:163], v225
	ds_read_b128 v[164:167], v225 offset:1024
	ds_read_b128 v[168:171], v225 offset:2048
	ds_read_b128 v[172:175], v225 offset:3072
	ds_read_b128 v[192:195], v225 offset:4096
	ds_read_b128 v[196:199], v225 offset:5120
	ds_read_b128 v[236:239], v225 offset:6144
	ds_read_b128 v[240:243], v225 offset:7168
	global_load_lds_dwordx4 v[244:245], off
	v_lshl_add_u64 v[244:245], s[10:11], 0, v[188:189]
	s_add_i32 m0, s37, 0xe000
	s_nop 0
	global_load_lds_dwordx4 v[244:245], off
	s_waitcnt vmcnt(8)
	s_waitcnt lgkmcnt(0)
	s_barrier
	s_setprio 1
	s_waitcnt lgkmcnt(0)
	v_mfma_f32_16x16x32_f16 v[140:143], v[112:115], v[160:163], v[140:143]
	v_mfma_f32_16x16x32_f16 v[136:139], v[124:127], v[160:163], v[136:139]
	v_mfma_f32_16x16x32_f16 v[108:111], v[112:115], v[168:171], v[108:111]
	v_mfma_f32_16x16x32_f16 v[104:107], v[124:127], v[168:171], v[104:107]
	v_mfma_f32_16x16x32_f16 v[92:95], v[112:115], v[192:195], v[92:95]
	v_mfma_f32_16x16x32_f16 v[88:91], v[124:127], v[192:195], v[88:91]
	v_mfma_f32_16x16x32_f16 v[76:79], v[112:115], v[236:239], v[76:79]
	v_mfma_f32_16x16x32_f16 v[72:75], v[124:127], v[236:239], v[72:75]
	v_mfma_f32_16x16x32_f16 v[140:143], v[116:119], v[164:167], v[140:143]
	v_mfma_f32_16x16x32_f16 v[136:139], v[128:131], v[164:167], v[136:139]
	v_mfma_f32_16x16x32_f16 v[108:111], v[116:119], v[172:175], v[108:111]
	v_mfma_f32_16x16x32_f16 v[104:107], v[128:131], v[172:175], v[104:107]
	v_mfma_f32_16x16x32_f16 v[92:95], v[116:119], v[196:199], v[92:95]
	v_mfma_f32_16x16x32_f16 v[88:91], v[128:131], v[196:199], v[88:91]
	v_mfma_f32_16x16x32_f16 v[76:79], v[116:119], v[240:243], v[76:79]
	v_mfma_f32_16x16x32_f16 v[72:75], v[128:131], v[240:243], v[72:75]
	s_setprio 0
	s_setprio 1
	v_mfma_f32_16x16x32_f16 v[132:135], v[144:147], v[160:163], v[132:135]
	v_mfma_f32_16x16x32_f16 v[120:123], v[152:155], v[160:163], v[120:123]
	v_mfma_f32_16x16x32_f16 v[100:103], v[144:147], v[168:171], v[100:103]
	v_mfma_f32_16x16x32_f16 v[96:99], v[152:155], v[168:171], v[96:99]
	v_mfma_f32_16x16x32_f16 v[84:87], v[144:147], v[192:195], v[84:87]
	v_mfma_f32_16x16x32_f16 v[80:83], v[152:155], v[192:195], v[80:83]
	v_mfma_f32_16x16x32_f16 v[68:71], v[144:147], v[236:239], v[68:71]
	v_mfma_f32_16x16x32_f16 v[64:67], v[152:155], v[236:239], v[64:67]
	v_mfma_f32_16x16x32_f16 v[132:135], v[148:151], v[164:167], v[132:135]
	v_mfma_f32_16x16x32_f16 v[120:123], v[156:159], v[164:167], v[120:123]
	v_mfma_f32_16x16x32_f16 v[100:103], v[148:151], v[172:175], v[100:103]
	v_mfma_f32_16x16x32_f16 v[96:99], v[156:159], v[172:175], v[96:99]
	v_mfma_f32_16x16x32_f16 v[84:87], v[148:151], v[196:199], v[84:87]
	v_mfma_f32_16x16x32_f16 v[80:83], v[156:159], v[196:199], v[80:83]
	v_mfma_f32_16x16x32_f16 v[68:71], v[148:151], v[240:243], v[68:71]
	v_mfma_f32_16x16x32_f16 v[64:67], v[156:159], v[240:243], v[64:67]
	s_setprio 0
	s_barrier
	s_add_i32 s10, s79, s36
	v_lshl_add_u64 v[244:245], s[26:27], 0, v[176:177]
	s_mov_b32 m0, s10
	ds_read_b128 v[160:163], v225 offset:16384
	ds_read_b128 v[164:167], v225 offset:17408
	ds_read_b128 v[168:171], v225 offset:18432
	ds_read_b128 v[172:175], v225 offset:19456
	ds_read_b128 v[192:195], v225 offset:20480
	ds_read_b128 v[196:199], v225 offset:21504
	ds_read_b128 v[236:239], v225 offset:22528
	ds_read_b128 v[240:243], v225 offset:23552
	global_load_lds_dwordx4 v[244:245], off
	s_add_i32 m0, s10, 0x2000
	s_add_u32 s10, s26, 0xb0000
	v_lshl_add_u64 v[246:247], s[26:27], 0, v[182:183]
	s_addc_u32 s11, s27, 0
	s_add_i32 s79, s85, s36
	global_load_lds_dwordx4 v[246:247], off
	v_lshl_add_u64 v[248:249], s[10:11], 0, v[176:177]
	s_mov_b32 m0, s79
	v_lshl_add_u64 v[250:251], s[28:29], 0, v[184:185]
	global_load_lds_dwordx4 v[248:249], off
	v_lshl_add_u64 v[248:249], s[10:11], 0, v[182:183]
	s_add_i32 m0, s79, 0x2000
	s_nop 0
	global_load_lds_dwordx4 v[248:249], off
	v_lshl_add_u64 v[248:249], s[28:29], 0, v[186:187]
	s_mov_b32 m0, s37
	s_nop 0
	global_load_lds_dwordx4 v[248:249], off
	s_mov_b32 m0, s42
	s_nop 0
	global_load_lds_dwordx4 v[250:251], off
	s_waitcnt vmcnt(8)
	s_waitcnt lgkmcnt(0)
	s_barrier
	s_setprio 1
	s_waitcnt lgkmcnt(0)
	v_mfma_f32_16x16x32_f16 v[60:63], v[112:115], v[160:163], v[60:63]
	v_mfma_f32_16x16x32_f16 v[56:59], v[124:127], v[160:163], v[56:59]
	v_mfma_f32_16x16x32_f16 v[44:47], v[112:115], v[168:171], v[44:47]
	v_mfma_f32_16x16x32_f16 v[40:43], v[124:127], v[168:171], v[40:43]
	v_mfma_f32_16x16x32_f16 v[28:31], v[112:115], v[192:195], v[28:31]
	v_mfma_f32_16x16x32_f16 v[24:27], v[124:127], v[192:195], v[24:27]
	v_mfma_f32_16x16x32_f16 v[12:15], v[112:115], v[236:239], v[12:15]
	v_mfma_f32_16x16x32_f16 v[8:11], v[124:127], v[236:239], v[8:11]
	v_mfma_f32_16x16x32_f16 v[60:63], v[116:119], v[164:167], v[60:63]
	v_mfma_f32_16x16x32_f16 v[56:59], v[128:131], v[164:167], v[56:59]
	v_mfma_f32_16x16x32_f16 v[44:47], v[116:119], v[172:175], v[44:47]
	v_mfma_f32_16x16x32_f16 v[40:43], v[128:131], v[172:175], v[40:43]
	v_mfma_f32_16x16x32_f16 v[28:31], v[116:119], v[196:199], v[28:31]
	v_mfma_f32_16x16x32_f16 v[24:27], v[128:131], v[196:199], v[24:27]
	v_mfma_f32_16x16x32_f16 v[12:15], v[116:119], v[240:243], v[12:15]
	v_mfma_f32_16x16x32_f16 v[8:11], v[128:131], v[240:243], v[8:11]
	s_setprio 0
	s_setprio 1
	v_mfma_f32_16x16x32_f16 v[52:55], v[144:147], v[160:163], v[52:55]
	v_mfma_f32_16x16x32_f16 v[48:51], v[152:155], v[160:163], v[48:51]
	v_mfma_f32_16x16x32_f16 v[36:39], v[144:147], v[168:171], v[36:39]
	v_mfma_f32_16x16x32_f16 v[32:35], v[152:155], v[168:171], v[32:35]
	v_mfma_f32_16x16x32_f16 v[20:23], v[144:147], v[192:195], v[20:23]
	v_mfma_f32_16x16x32_f16 v[16:19], v[152:155], v[192:195], v[16:19]
	v_mfma_f32_16x16x32_f16 v[4:7], v[144:147], v[236:239], v[4:7]
	v_mfma_f32_16x16x32_f16 v[0:3], v[152:155], v[236:239], v[0:3]
	v_mfma_f32_16x16x32_f16 v[52:55], v[148:151], v[164:167], v[52:55]
	v_mfma_f32_16x16x32_f16 v[48:51], v[156:159], v[164:167], v[48:51]
	v_mfma_f32_16x16x32_f16 v[36:39], v[148:151], v[172:175], v[36:39]
	v_mfma_f32_16x16x32_f16 v[32:35], v[156:159], v[172:175], v[32:35]
	v_mfma_f32_16x16x32_f16 v[20:23], v[148:151], v[196:199], v[20:23]
	v_mfma_f32_16x16x32_f16 v[16:19], v[156:159], v[196:199], v[16:19]
	v_mfma_f32_16x16x32_f16 v[4:7], v[148:151], v[240:243], v[4:7]
	v_mfma_f32_16x16x32_f16 v[0:3], v[156:159], v[240:243], v[0:3]
	s_setprio 0
	s_barrier
	s_add_i32 s79, 0, 0x18000
	s_add_i32 s85, 0, 0x1c000
	v_add_u32_e32 v128, s79, v211
	v_add_u32_e32 v156, s85, v211
	ds_read_b128 v[112:115], v128
	ds_read_b128 v[116:119], v128 offset:1024
	ds_read_b128 v[124:127], v128 offset:2048
	ds_read_b128 v[128:131], v128 offset:3072
	ds_read_b128 v[144:147], v156
	ds_read_b128 v[148:151], v156 offset:1024
	ds_read_b128 v[152:155], v156 offset:2048
	ds_read_b128 v[156:159], v156 offset:3072
	s_add_u32 s10, s28, 0x4000
	s_addc_u32 s11, s29, 0
	s_mov_b32 m0, s43
	v_lshl_add_u64 v[252:253], s[10:11], 0, v[186:187]
	ds_read_b128 v[160:163], v225 offset:32768
	ds_read_b128 v[164:167], v225 offset:33792
	ds_read_b128 v[168:171], v225 offset:34816
	ds_read_b128 v[172:175], v225 offset:35840
	ds_read_b128 v[192:195], v225 offset:36864
	ds_read_b128 v[196:199], v225 offset:37888
	ds_read_b128 v[236:239], v225 offset:38912
	ds_read_b128 v[240:243], v225 offset:39936
	global_load_lds_dwordx4 v[252:253], off
	v_lshl_add_u64 v[252:253], s[10:11], 0, v[184:185]
	s_mov_b32 m0, s50
	s_nop 0
	global_load_lds_dwordx4 v[252:253], off
	s_waitcnt vmcnt(8)
	s_waitcnt lgkmcnt(0)
	s_barrier
	s_setprio 1
	s_waitcnt lgkmcnt(0)
	v_mfma_f32_16x16x32_f16 v[140:143], v[112:115], v[160:163], v[140:143]
	v_mfma_f32_16x16x32_f16 v[136:139], v[124:127], v[160:163], v[136:139]
	v_mfma_f32_16x16x32_f16 v[108:111], v[112:115], v[168:171], v[108:111]
	v_mfma_f32_16x16x32_f16 v[104:107], v[124:127], v[168:171], v[104:107]
	v_mfma_f32_16x16x32_f16 v[92:95], v[112:115], v[192:195], v[92:95]
	v_mfma_f32_16x16x32_f16 v[88:91], v[124:127], v[192:195], v[88:91]
	v_mfma_f32_16x16x32_f16 v[76:79], v[112:115], v[236:239], v[76:79]
	v_mfma_f32_16x16x32_f16 v[72:75], v[124:127], v[236:239], v[72:75]
	v_mfma_f32_16x16x32_f16 v[140:143], v[116:119], v[164:167], v[140:143]
	v_mfma_f32_16x16x32_f16 v[136:139], v[128:131], v[164:167], v[136:139]
	v_mfma_f32_16x16x32_f16 v[108:111], v[116:119], v[172:175], v[108:111]
	v_mfma_f32_16x16x32_f16 v[104:107], v[128:131], v[172:175], v[104:107]
	v_mfma_f32_16x16x32_f16 v[92:95], v[116:119], v[196:199], v[92:95]
	v_mfma_f32_16x16x32_f16 v[88:91], v[128:131], v[196:199], v[88:91]
	v_mfma_f32_16x16x32_f16 v[76:79], v[116:119], v[240:243], v[76:79]
	v_mfma_f32_16x16x32_f16 v[72:75], v[128:131], v[240:243], v[72:75]
	s_setprio 0
	s_setprio 1
	v_mfma_f32_16x16x32_f16 v[132:135], v[144:147], v[160:163], v[132:135]
	v_mfma_f32_16x16x32_f16 v[120:123], v[152:155], v[160:163], v[120:123]
	v_mfma_f32_16x16x32_f16 v[100:103], v[144:147], v[168:171], v[100:103]
	v_mfma_f32_16x16x32_f16 v[96:99], v[152:155], v[168:171], v[96:99]
	v_mfma_f32_16x16x32_f16 v[84:87], v[144:147], v[192:195], v[84:87]
	v_mfma_f32_16x16x32_f16 v[80:83], v[152:155], v[192:195], v[80:83]
	v_mfma_f32_16x16x32_f16 v[68:71], v[144:147], v[236:239], v[68:71]
	v_mfma_f32_16x16x32_f16 v[64:67], v[152:155], v[236:239], v[64:67]
	v_mfma_f32_16x16x32_f16 v[132:135], v[148:151], v[164:167], v[132:135]
	v_mfma_f32_16x16x32_f16 v[120:123], v[156:159], v[164:167], v[120:123]
	v_mfma_f32_16x16x32_f16 v[100:103], v[148:151], v[172:175], v[100:103]
	v_mfma_f32_16x16x32_f16 v[96:99], v[156:159], v[172:175], v[96:99]
	v_mfma_f32_16x16x32_f16 v[84:87], v[148:151], v[196:199], v[84:87]
	v_mfma_f32_16x16x32_f16 v[80:83], v[156:159], v[196:199], v[80:83]
	v_mfma_f32_16x16x32_f16 v[68:71], v[148:151], v[240:243], v[68:71]
	v_mfma_f32_16x16x32_f16 v[64:67], v[156:159], v[240:243], v[64:67]
	s_setprio 0
	s_barrier
	s_add_i32 s10, s79, s36
	v_lshl_add_u64 v[244:245], v[244:245], 0, s[72:73]
	s_mov_b32 m0, s10
	ds_read_b128 v[160:163], v225 offset:49152
	ds_read_b128 v[164:167], v225 offset:50176
	ds_read_b128 v[168:171], v225 offset:51200
	ds_read_b128 v[172:175], v225 offset:52224
	ds_read_b128 v[192:195], v225 offset:53248
	ds_read_b128 v[196:199], v225 offset:54272
	ds_read_b128 v[236:239], v225 offset:55296
	ds_read_b128 v[240:243], v225 offset:56320
	global_load_lds_dwordx4 v[244:245], off
	s_add_i32 m0, s10, 0x2000
	s_add_u32 s10, s26, 0xb0080
	v_lshl_add_u64 v[244:245], v[246:247], 0, s[72:73]
	s_addc_u32 s11, s27, 0
	s_add_i32 s26, s85, s36
	global_load_lds_dwordx4 v[244:245], off
	v_lshl_add_u64 v[244:245], s[10:11], 0, v[176:177]
	s_mov_b32 m0, s26
	s_nop 0
	global_load_lds_dwordx4 v[244:245], off
	v_lshl_add_u64 v[244:245], s[10:11], 0, v[182:183]
	s_add_i32 m0, s26, 0x2000
	s_nop 0
	global_load_lds_dwordx4 v[244:245], off
	v_lshl_add_u64 v[244:245], v[248:249], 0, s[98:99]
	s_mov_b32 m0, s51
	s_nop 0
	global_load_lds_dwordx4 v[244:245], off
	v_lshl_add_u64 v[244:245], v[250:251], 0, s[98:99]
	s_mov_b32 m0, s54
	s_nop 0
	global_load_lds_dwordx4 v[244:245], off
	s_waitcnt vmcnt(8)
	s_waitcnt lgkmcnt(0)
	s_barrier
	s_setprio 1
	s_waitcnt lgkmcnt(0)
	v_mfma_f32_16x16x32_f16 v[60:63], v[112:115], v[160:163], v[60:63]
	v_mfma_f32_16x16x32_f16 v[56:59], v[124:127], v[160:163], v[56:59]
	v_mfma_f32_16x16x32_f16 v[44:47], v[112:115], v[168:171], v[44:47]
	v_mfma_f32_16x16x32_f16 v[40:43], v[124:127], v[168:171], v[40:43]
	v_mfma_f32_16x16x32_f16 v[28:31], v[112:115], v[192:195], v[28:31]
	v_mfma_f32_16x16x32_f16 v[24:27], v[124:127], v[192:195], v[24:27]
	v_mfma_f32_16x16x32_f16 v[12:15], v[112:115], v[236:239], v[12:15]
	v_mfma_f32_16x16x32_f16 v[8:11], v[124:127], v[236:239], v[8:11]
	v_mfma_f32_16x16x32_f16 v[60:63], v[116:119], v[164:167], v[60:63]
	v_mfma_f32_16x16x32_f16 v[56:59], v[128:131], v[164:167], v[56:59]
	v_mfma_f32_16x16x32_f16 v[44:47], v[116:119], v[172:175], v[44:47]
	v_mfma_f32_16x16x32_f16 v[40:43], v[128:131], v[172:175], v[40:43]
	v_mfma_f32_16x16x32_f16 v[28:31], v[116:119], v[196:199], v[28:31]
	v_mfma_f32_16x16x32_f16 v[24:27], v[128:131], v[196:199], v[24:27]
	v_mfma_f32_16x16x32_f16 v[12:15], v[116:119], v[240:243], v[12:15]
	v_mfma_f32_16x16x32_f16 v[8:11], v[128:131], v[240:243], v[8:11]
	s_setprio 0
	s_setprio 1
	v_mfma_f32_16x16x32_f16 v[52:55], v[144:147], v[160:163], v[52:55]
	v_mfma_f32_16x16x32_f16 v[48:51], v[152:155], v[160:163], v[48:51]
	v_mfma_f32_16x16x32_f16 v[36:39], v[144:147], v[168:171], v[36:39]
	v_mfma_f32_16x16x32_f16 v[32:35], v[152:155], v[168:171], v[32:35]
	v_mfma_f32_16x16x32_f16 v[20:23], v[144:147], v[192:195], v[20:23]
	v_mfma_f32_16x16x32_f16 v[16:19], v[152:155], v[192:195], v[16:19]
	v_mfma_f32_16x16x32_f16 v[4:7], v[144:147], v[236:239], v[4:7]
	v_mfma_f32_16x16x32_f16 v[0:3], v[152:155], v[236:239], v[0:3]
	v_mfma_f32_16x16x32_f16 v[52:55], v[148:151], v[164:167], v[52:55]
	v_mfma_f32_16x16x32_f16 v[48:51], v[156:159], v[164:167], v[48:51]
	v_mfma_f32_16x16x32_f16 v[36:39], v[148:151], v[172:175], v[36:39]
	v_mfma_f32_16x16x32_f16 v[32:35], v[156:159], v[172:175], v[32:35]
	v_mfma_f32_16x16x32_f16 v[20:23], v[148:151], v[196:199], v[20:23]
	v_mfma_f32_16x16x32_f16 v[16:19], v[156:159], v[196:199], v[16:19]
	v_mfma_f32_16x16x32_f16 v[4:7], v[148:151], v[240:243], v[4:7]
	v_mfma_f32_16x16x32_f16 v[0:3], v[156:159], v[240:243], v[0:3]
	s_setprio 0
	s_barrier
	s_add_i32 s53, s53, 2
	s_add_u32 s71, s71, 0x100
	s_addc_u32 s78, s78, 0
	s_cmp_gt_u32 s53, 41
	s_mov_b64 s[10:11], s[0:1]
	s_cbranch_scc0 .LBB0_474
	s_and_b64 vcc, exec, s[16:17]
	s_cbranch_vccz .LBB0_477
	s_barrier

.LBB0_577:
	ds_read2_b32 v[150:151], v146 offset1:16
	v_pk_mul_f32 v[120:121], v[124:125], v[120:121]
	v_pk_mul_f32 v[112:113], v[116:117], v[112:113]
	v_pk_mul_f32 v[114:115], v[118:119], v[114:115]
	v_pk_mul_f32 v[122:123], v[126:127], v[122:123]
	s_waitcnt lgkmcnt(0)
	v_mul_f32_e32 v149, 0xbfb8aa3b, v150
	v_mul_f32_e32 v152, v150, v150
	v_mul_f32_e32 v150, v124, v149
	v_mul_f32_e32 v153, v116, v149
	v_exp_f32_e32 v150, v150
	v_mul_f32_e32 v154, v125, v149
	v_exp_f32_e32 v153, v153
	v_exp_f32_e32 v155, v154
	v_add_f32_e32 v150, 1.0, v150
	v_rcp_f32_e32 v154, v150
	v_add_f32_e32 v150, 1.0, v153
	v_add_f32_e32 v153, 1.0, v155
	v_rcp_f32_e32 v156, v150
	v_mul_f32_e32 v150, v117, v149
	v_rcp_f32_e32 v155, v153
	v_exp_f32_e32 v150, v150
	v_mul_f32_e32 v116, v126, v149
	v_mul_f32_e32 v119, v119, v149
	v_pk_mul_f32 v[124:125], v[152:153], v[154:155] op_sel_hi:[0,1]
	v_pk_mul_f32 v[120:121], v[120:121], v[124:125]
	v_add_f32_e32 v124, 1.0, v150
	v_rcp_f32_e32 v157, v124
	v_exp_f32_e32 v124, v116
	v_mul_f32_e32 v116, v118, v149
	v_exp_f32_e32 v125, v116
	v_exp_f32_e32 v126, v119
	v_add_f32_e32 v118, 1.0, v124
	v_rcp_f32_e32 v118, v118
	v_add_f32_e32 v124, 1.0, v125
	v_mul_f32_e32 v125, v127, v149
	v_exp_f32_e32 v125, v125
	v_rcp_f32_e32 v124, v124
	v_pk_mul_f32 v[116:117], v[152:153], v[156:157] op_sel_hi:[0,1]
	v_pk_mul_f32 v[116:117], v[112:113], v[116:117]
	v_add_f32_e32 v119, 1.0, v125
	v_rcp_f32_e32 v119, v119
	v_add_f32_e32 v125, 1.0, v126
	v_rcp_f32_e32 v125, v125
	v_lshl_add_u32 v148, s42, 8, v142
	v_pk_mul_f32 v[112:113], v[152:153], v[118:119] op_sel_hi:[0,1]
	v_pk_mul_f32 v[118:119], v[122:123], v[112:113]
	v_pk_mul_f32 v[112:113], v[152:153], v[124:125] op_sel_hi:[0,1]
	v_pk_mul_f32 v[122:123], v[114:115], v[112:113]
	s_mul_i32 s18, s42, 0x160000
	s_lshl_b32 s19, s37, 16
	s_add_u32 s18, s18, s19
	s_add_u32 s18, s48, s18
	s_addc_u32 s19, s49, 0
	v_and_b32_e32 v114, 0x7f, v176
	v_and_b32_e32 v115, 0x80, v176
	v_lshl_add_u32 v114, v115, 8, v114
	v_lshl_add_u32 v114, v142, 7, v114
	v_mov_b32_e32 v115, 0
	v_lshl_add_u64 v[124:125], s[18:19], 0, v[114:115]
	v_mov_b32_e32 v210, v124
	v_mov_b32_e32 v211, v125
	v_cvt_pk_f16_f32 v114, v120, v121
	v_cvt_pk_f16_f32 v115, v118, v119
	v_cvt_pk_f16_f32 v116, v116, v117
	v_cvt_pk_f16_f32 v117, v122, v123
	v_mul_f32_e32 v120, 0xbfb8aa3b, v151
	ds_read2_b32 v[140:141], v146 offset0:32 offset1:48
	flat_store_dwordx4 v[124:125], v[114:117]
	v_mul_f32_e32 v118, v109, v120
	v_exp_f32_e32 v119, v118
	v_mul_f32_e32 v117, v100, v120
	v_mul_f32_e32 v114, v108, v120
	v_exp_f32_e32 v117, v117
	v_exp_f32_e32 v116, v114
	v_mul_f32_e32 v121, v101, v120
	v_add_f32_e32 v117, 1.0, v117
	v_add_f32_e32 v116, 1.0, v116
	v_rcp_f32_e32 v118, v117
	v_add_f32_e32 v117, 1.0, v119
	v_rcp_f32_e32 v116, v116
	v_rcp_f32_e32 v117, v117
	v_exp_f32_e32 v119, v121
	v_mul_f32_e32 v114, v151, v151
	v_pk_mul_f32 v[104:105], v[108:109], v[104:105]
	v_pk_mul_f32 v[108:109], v[114:115], v[116:117] op_sel_hi:[0,1]
	v_pk_mul_f32 v[104:105], v[104:105], v[108:109]
	v_add_f32_e32 v108, 1.0, v119
	v_pk_mul_f32 v[96:97], v[100:101], v[96:97]
	v_mul_f32_e32 v100, v110, v120
	v_rcp_f32_e32 v119, v108
	v_exp_f32_e32 v108, v100
	v_mul_f32_e32 v100, v102, v120
	v_exp_f32_e32 v109, v100
	v_pk_mul_f32 v[98:99], v[102:103], v[98:99]
	v_add_f32_e32 v102, 1.0, v108
	v_mul_f32_e32 v103, v103, v120
	v_add_f32_e32 v108, 1.0, v109
	v_mul_f32_e32 v109, v111, v120
	v_exp_f32_e32 v109, v109
	v_pk_mul_f32 v[106:107], v[110:111], v[106:107]
	v_exp_f32_e32 v110, v103
	v_rcp_f32_e32 v102, v102
	v_add_f32_e32 v103, 1.0, v109
	v_rcp_f32_e32 v103, v103
	v_add_f32_e32 v109, 1.0, v110
	v_rcp_f32_e32 v108, v108
	v_rcp_f32_e32 v109, v109
	v_pk_mul_f32 v[100:101], v[114:115], v[118:119] op_sel_hi:[0,1]
	v_pk_mul_f32 v[100:101], v[96:97], v[100:101]
	v_pk_mul_f32 v[96:97], v[114:115], v[102:103] op_sel_hi:[0,1]
	v_pk_mul_f32 v[102:103], v[106:107], v[96:97]
	v_pk_mul_f32 v[96:97], v[114:115], v[108:109] op_sel_hi:[0,1]
	v_pk_mul_f32 v[106:107], v[98:99], v[96:97]
	v_cvt_pk_f16_f32 v96, v104, v105
	v_cvt_pk_f16_f32 v97, v102, v103
	v_cvt_pk_f16_f32 v98, v100, v101
	v_cvt_pk_f16_f32 v99, v106, v107
	s_waitcnt lgkmcnt(0)
	v_mul_f32_e32 v102, 0xbfb8aa3b, v140
	v_add_co_u32_e32 v210, vcc, 0x800, v210
	v_addc_co_u32_e32 v211, vcc, 0, v211, vcc
	flat_store_dwordx4 v[210:211], v[96:99]
	v_mul_f32_e32 v100, v93, v102
	v_exp_f32_e32 v101, v100
	v_mul_f32_e32 v99, v84, v102
	v_mul_f32_e32 v96, v92, v102
	v_exp_f32_e32 v99, v99
	v_exp_f32_e32 v98, v96
	v_mul_f32_e32 v103, v85, v102
	v_add_f32_e32 v99, 1.0, v99
	v_add_f32_e32 v98, 1.0, v98
	v_rcp_f32_e32 v100, v99
	v_add_f32_e32 v99, 1.0, v101
	v_rcp_f32_e32 v98, v98
	v_rcp_f32_e32 v99, v99
	v_exp_f32_e32 v101, v103
	v_mul_f32_e32 v96, v140, v140
	v_pk_mul_f32 v[88:89], v[92:93], v[88:89]
	v_pk_mul_f32 v[92:93], v[96:97], v[98:99] op_sel_hi:[0,1]
	v_pk_mul_f32 v[88:89], v[88:89], v[92:93]
	v_add_f32_e32 v92, 1.0, v101
	v_pk_mul_f32 v[80:81], v[84:85], v[80:81]
	v_mul_f32_e32 v84, v94, v102
	v_rcp_f32_e32 v101, v92
	v_exp_f32_e32 v92, v84
	v_mul_f32_e32 v84, v86, v102
	v_exp_f32_e32 v93, v84
	v_pk_mul_f32 v[82:83], v[86:87], v[82:83]
	v_add_f32_e32 v86, 1.0, v92
	v_mul_f32_e32 v87, v87, v102
	v_add_f32_e32 v92, 1.0, v93
	v_mul_f32_e32 v93, v95, v102
	v_exp_f32_e32 v93, v93
	v_pk_mul_f32 v[90:91], v[94:95], v[90:91]
	v_exp_f32_e32 v94, v87
	v_rcp_f32_e32 v86, v86
	v_add_f32_e32 v87, 1.0, v93
	v_rcp_f32_e32 v87, v87
	v_add_f32_e32 v93, 1.0, v94
	v_rcp_f32_e32 v92, v92
	v_rcp_f32_e32 v93, v93
	v_pk_mul_f32 v[84:85], v[96:97], v[100:101] op_sel_hi:[0,1]
	v_pk_mul_f32 v[84:85], v[80:81], v[84:85]
	v_pk_mul_f32 v[80:81], v[96:97], v[86:87] op_sel_hi:[0,1]
	v_pk_mul_f32 v[86:87], v[90:91], v[80:81]
	v_pk_mul_f32 v[80:81], v[96:97], v[92:93] op_sel_hi:[0,1]
	v_pk_mul_f32 v[90:91], v[82:83], v[80:81]
	v_cvt_pk_f16_f32 v80, v88, v89
	v_cvt_pk_f16_f32 v81, v86, v87
	v_cvt_pk_f16_f32 v82, v84, v85
	v_cvt_pk_f16_f32 v83, v90, v91
	v_mul_f32_e32 v86, 0xbfb8aa3b, v141
	v_add_co_u32_e32 v210, vcc, 0x800, v210
	v_addc_co_u32_e32 v211, vcc, 0, v211, vcc
	flat_store_dwordx4 v[210:211], v[80:83]
	v_mul_f32_e32 v84, v77, v86
	v_exp_f32_e32 v85, v84
	v_mul_f32_e32 v83, v68, v86
	v_mul_f32_e32 v80, v76, v86
	v_exp_f32_e32 v83, v83
	v_exp_f32_e32 v82, v80
	v_mul_f32_e32 v87, v69, v86
	v_add_f32_e32 v83, 1.0, v83
	v_add_f32_e32 v82, 1.0, v82
	v_rcp_f32_e32 v84, v83
	v_add_f32_e32 v83, 1.0, v85
	v_rcp_f32_e32 v82, v82
	v_rcp_f32_e32 v83, v83
	v_exp_f32_e32 v85, v87
	v_mul_f32_e32 v80, v141, v141
	v_pk_mul_f32 v[72:73], v[76:77], v[72:73]
	v_pk_mul_f32 v[76:77], v[80:81], v[82:83] op_sel_hi:[0,1]
	v_pk_mul_f32 v[72:73], v[72:73], v[76:77]
	v_add_f32_e32 v76, 1.0, v85
	v_pk_mul_f32 v[64:65], v[68:69], v[64:65]
	v_mul_f32_e32 v68, v78, v86
	v_rcp_f32_e32 v85, v76
	v_exp_f32_e32 v76, v68
	v_mul_f32_e32 v68, v70, v86
	v_exp_f32_e32 v77, v68
	v_pk_mul_f32 v[66:67], v[70:71], v[66:67]
	v_add_f32_e32 v70, 1.0, v76
	v_mul_f32_e32 v71, v71, v86
	v_add_f32_e32 v76, 1.0, v77
	v_mul_f32_e32 v77, v79, v86
	v_exp_f32_e32 v77, v77
	v_pk_mul_f32 v[74:75], v[78:79], v[74:75]
	v_exp_f32_e32 v78, v71
	v_rcp_f32_e32 v70, v70
	v_add_f32_e32 v71, 1.0, v77
	v_rcp_f32_e32 v71, v71
	v_add_f32_e32 v77, 1.0, v78
	v_rcp_f32_e32 v76, v76
	v_rcp_f32_e32 v77, v77
	v_pk_mul_f32 v[68:69], v[80:81], v[84:85] op_sel_hi:[0,1]
	v_pk_mul_f32 v[68:69], v[64:65], v[68:69]
	v_pk_mul_f32 v[64:65], v[80:81], v[70:71] op_sel_hi:[0,1]
	v_pk_mul_f32 v[70:71], v[74:75], v[64:65]
	v_pk_mul_f32 v[64:65], v[80:81], v[76:77] op_sel_hi:[0,1]
	v_pk_mul_f32 v[74:75], v[66:67], v[64:65]
	v_cvt_pk_f16_f32 v64, v72, v73
	v_cvt_pk_f16_f32 v65, v70, v71
	v_cvt_pk_f16_f32 v66, v68, v69
	v_cvt_pk_f16_f32 v67, v74, v75
	v_add_co_u32_e32 v210, vcc, 0x800, v210
	v_addc_co_u32_e32 v211, vcc, 0, v211, vcc
	flat_store_dwordx4 v[210:211], v[64:67]
	ds_read2_b32 v[66:67], v146 offset0:128 offset1:144
	ds_read2_b32 v[64:65], v146 offset0:160 offset1:176
	v_pk_mul_f32 v[56:57], v[60:61], v[56:57]
	v_pk_mul_f32 v[48:49], v[52:53], v[48:49]
	v_pk_mul_f32 v[50:51], v[54:55], v[50:51]
	s_waitcnt lgkmcnt(0)
	v_mul_f32_e32 v73, 0xbfb8aa3b, v66
	v_mul_f32_e32 v69, v52, v73
	v_mul_f32_e32 v68, v60, v73
	v_exp_f32_e32 v69, v69
	v_mul_f32_e32 v70, v61, v73
	v_exp_f32_e32 v68, v68
	v_exp_f32_e32 v71, v70
	v_add_f32_e32 v69, 1.0, v69
	v_rcp_f32_e32 v70, v69
	v_add_f32_e32 v68, 1.0, v68
	v_add_f32_e32 v69, 1.0, v71
	v_rcp_f32_e32 v68, v68
	v_mul_f32_e32 v74, v53, v73
	v_rcp_f32_e32 v69, v69
	v_exp_f32_e32 v71, v74
	v_mul_f32_e32 v66, v66, v66
	v_mul_f32_e32 v52, v62, v73
	v_pk_mul_f32 v[60:61], v[66:67], v[68:69] op_sel_hi:[0,1]
	v_pk_mul_f32 v[56:57], v[56:57], v[60:61]
	v_add_f32_e32 v60, 1.0, v71
	v_rcp_f32_e32 v71, v60
	v_exp_f32_e32 v60, v52
	v_mul_f32_e32 v52, v54, v73
	v_exp_f32_e32 v61, v52
	v_mul_f32_e32 v55, v55, v73
	v_add_f32_e32 v54, 1.0, v60
	v_pk_mul_f32 v[58:59], v[62:63], v[58:59]
	v_add_f32_e32 v60, 1.0, v61
	v_mul_f32_e32 v61, v63, v73
	v_exp_f32_e32 v61, v61
	v_exp_f32_e32 v62, v55
	v_rcp_f32_e32 v54, v54
	v_rcp_f32_e32 v60, v60
	v_add_f32_e32 v55, 1.0, v61
	v_rcp_f32_e32 v55, v55
	v_add_f32_e32 v61, 1.0, v62
	v_rcp_f32_e32 v61, v61
	v_pk_mul_f32 v[52:53], v[66:67], v[70:71] op_sel_hi:[0,1]
	v_pk_mul_f32 v[52:53], v[48:49], v[52:53]
	v_pk_mul_f32 v[48:49], v[66:67], v[54:55] op_sel_hi:[0,1]
	v_pk_mul_f32 v[54:55], v[58:59], v[48:49]
	v_pk_mul_f32 v[48:49], v[66:67], v[60:61] op_sel_hi:[0,1]
	v_pk_mul_f32 v[58:59], v[50:51], v[48:49]
	v_cvt_pk_f16_f32 v48, v56, v57
	v_cvt_pk_f16_f32 v49, v54, v55
	v_cvt_pk_f16_f32 v50, v52, v53
	v_cvt_pk_f16_f32 v51, v58, v59
	v_mul_f32_e32 v54, 0xbfb8aa3b, v67
	v_add_co_u32_e32 v210, vcc, 0x2800, v210
	v_addc_co_u32_e32 v211, vcc, 0, v211, vcc
	flat_store_dwordx4 v[210:211], v[48:51]
	v_mul_f32_e32 v52, v45, v54
	v_exp_f32_e32 v53, v52
	v_mul_f32_e32 v51, v36, v54
	v_mul_f32_e32 v48, v44, v54
	v_exp_f32_e32 v51, v51
	v_exp_f32_e32 v50, v48
	v_mul_f32_e32 v55, v37, v54
	v_add_f32_e32 v51, 1.0, v51
	v_add_f32_e32 v50, 1.0, v50
	v_rcp_f32_e32 v52, v51
	v_add_f32_e32 v51, 1.0, v53
	v_rcp_f32_e32 v50, v50
	v_rcp_f32_e32 v51, v51
	v_exp_f32_e32 v53, v55
	v_mul_f32_e32 v48, v67, v67
	v_pk_mul_f32 v[40:41], v[44:45], v[40:41]
	v_pk_mul_f32 v[44:45], v[48:49], v[50:51] op_sel_hi:[0,1]
	v_pk_mul_f32 v[40:41], v[40:41], v[44:45]
	v_add_f32_e32 v44, 1.0, v53
	v_pk_mul_f32 v[32:33], v[36:37], v[32:33]
	v_mul_f32_e32 v36, v46, v54
	v_rcp_f32_e32 v53, v44
	v_exp_f32_e32 v44, v36
	v_mul_f32_e32 v36, v38, v54
	v_exp_f32_e32 v45, v36
	v_pk_mul_f32 v[34:35], v[38:39], v[34:35]
	v_add_f32_e32 v38, 1.0, v44
	v_mul_f32_e32 v39, v39, v54
	v_add_f32_e32 v44, 1.0, v45
	v_mul_f32_e32 v45, v47, v54
	v_exp_f32_e32 v45, v45
	v_pk_mul_f32 v[42:43], v[46:47], v[42:43]
	v_exp_f32_e32 v46, v39
	v_rcp_f32_e32 v38, v38
	v_add_f32_e32 v39, 1.0, v45
	v_rcp_f32_e32 v39, v39
	v_add_f32_e32 v45, 1.0, v46
	v_rcp_f32_e32 v44, v44
	v_rcp_f32_e32 v45, v45
	v_pk_mul_f32 v[36:37], v[48:49], v[52:53] op_sel_hi:[0,1]
	v_pk_mul_f32 v[36:37], v[32:33], v[36:37]
	v_pk_mul_f32 v[32:33], v[48:49], v[38:39] op_sel_hi:[0,1]
	v_pk_mul_f32 v[38:39], v[42:43], v[32:33]
	v_pk_mul_f32 v[32:33], v[48:49], v[44:45] op_sel_hi:[0,1]
	v_pk_mul_f32 v[42:43], v[34:35], v[32:33]
	v_cvt_pk_f16_f32 v32, v40, v41
	v_cvt_pk_f16_f32 v33, v38, v39
	v_cvt_pk_f16_f32 v34, v36, v37
	v_cvt_pk_f16_f32 v35, v42, v43
	v_mul_f32_e32 v38, 0xbfb8aa3b, v64
	v_add_co_u32_e32 v210, vcc, 0x800, v210
	v_addc_co_u32_e32 v211, vcc, 0, v211, vcc
	flat_store_dwordx4 v[210:211], v[32:35]
	v_mul_f32_e32 v36, v29, v38
	v_exp_f32_e32 v37, v36
	v_mul_f32_e32 v35, v20, v38
	v_mul_f32_e32 v32, v28, v38
	v_exp_f32_e32 v35, v35
	v_exp_f32_e32 v34, v32
	v_mul_f32_e32 v39, v21, v38
	v_add_f32_e32 v35, 1.0, v35
	v_add_f32_e32 v34, 1.0, v34
	v_rcp_f32_e32 v36, v35
	v_add_f32_e32 v35, 1.0, v37
	v_rcp_f32_e32 v34, v34
	v_rcp_f32_e32 v35, v35
	v_exp_f32_e32 v37, v39
	v_mul_f32_e32 v32, v64, v64
	v_pk_mul_f32 v[24:25], v[28:29], v[24:25]
	v_pk_mul_f32 v[28:29], v[32:33], v[34:35] op_sel_hi:[0,1]
	v_pk_mul_f32 v[24:25], v[24:25], v[28:29]
	v_add_f32_e32 v28, 1.0, v37
	v_pk_mul_f32 v[16:17], v[20:21], v[16:17]
	v_mul_f32_e32 v20, v30, v38
	v_rcp_f32_e32 v37, v28
	v_exp_f32_e32 v28, v20
	v_mul_f32_e32 v20, v22, v38
	v_exp_f32_e32 v29, v20
	v_pk_mul_f32 v[18:19], v[22:23], v[18:19]
	v_add_f32_e32 v22, 1.0, v28
	v_mul_f32_e32 v23, v23, v38
	v_add_f32_e32 v28, 1.0, v29
	v_mul_f32_e32 v29, v31, v38
	v_exp_f32_e32 v29, v29
	v_pk_mul_f32 v[26:27], v[30:31], v[26:27]
	v_exp_f32_e32 v30, v23
	v_rcp_f32_e32 v22, v22
	v_add_f32_e32 v23, 1.0, v29
	v_rcp_f32_e32 v23, v23
	v_add_f32_e32 v29, 1.0, v30
	v_rcp_f32_e32 v28, v28
	v_rcp_f32_e32 v29, v29
	v_pk_mul_f32 v[20:21], v[32:33], v[36:37] op_sel_hi:[0,1]
	v_pk_mul_f32 v[20:21], v[16:17], v[20:21]
	v_pk_mul_f32 v[16:17], v[32:33], v[22:23] op_sel_hi:[0,1]
	v_pk_mul_f32 v[22:23], v[26:27], v[16:17]
	v_pk_mul_f32 v[16:17], v[32:33], v[28:29] op_sel_hi:[0,1]
	v_pk_mul_f32 v[26:27], v[18:19], v[16:17]
	v_cvt_pk_f16_f32 v16, v24, v25
	v_cvt_pk_f16_f32 v17, v22, v23
	v_cvt_pk_f16_f32 v18, v20, v21
	v_cvt_pk_f16_f32 v19, v26, v27
	v_mul_f32_e32 v22, 0xbfb8aa3b, v65
	v_add_co_u32_e32 v210, vcc, 0x800, v210
	v_addc_co_u32_e32 v211, vcc, 0, v211, vcc
	flat_store_dwordx4 v[210:211], v[16:19]
	v_mul_f32_e32 v20, v13, v22
	v_exp_f32_e32 v21, v20
	v_mul_f32_e32 v19, v4, v22
	v_mul_f32_e32 v16, v12, v22
	v_exp_f32_e32 v19, v19
	v_exp_f32_e32 v18, v16
	v_mul_f32_e32 v23, v5, v22
	v_add_f32_e32 v19, 1.0, v19
	v_add_f32_e32 v18, 1.0, v18
	v_rcp_f32_e32 v20, v19
	v_add_f32_e32 v19, 1.0, v21
	v_rcp_f32_e32 v18, v18
	v_rcp_f32_e32 v19, v19
	v_exp_f32_e32 v21, v23
	v_mul_f32_e32 v16, v65, v65
	v_pk_mul_f32 v[8:9], v[12:13], v[8:9]
	v_pk_mul_f32 v[12:13], v[16:17], v[18:19] op_sel_hi:[0,1]
	v_pk_mul_f32 v[8:9], v[8:9], v[12:13]
	v_add_f32_e32 v12, 1.0, v21
	v_pk_mul_f32 v[0:1], v[4:5], v[0:1]
	v_mul_f32_e32 v4, v14, v22
	v_rcp_f32_e32 v21, v12
	v_exp_f32_e32 v12, v4
	v_mul_f32_e32 v4, v6, v22
	v_exp_f32_e32 v13, v4
	v_pk_mul_f32 v[2:3], v[6:7], v[2:3]
	v_add_f32_e32 v6, 1.0, v12
	v_mul_f32_e32 v7, v7, v22
	v_add_f32_e32 v12, 1.0, v13
	v_mul_f32_e32 v13, v15, v22
	v_exp_f32_e32 v13, v13
	v_pk_mul_f32 v[10:11], v[14:15], v[10:11]
	v_exp_f32_e32 v14, v7
	v_rcp_f32_e32 v6, v6
	v_add_f32_e32 v7, 1.0, v13
	v_rcp_f32_e32 v7, v7
	v_add_f32_e32 v13, 1.0, v14
	v_rcp_f32_e32 v12, v12
	v_rcp_f32_e32 v13, v13
	v_pk_mul_f32 v[4:5], v[16:17], v[20:21] op_sel_hi:[0,1]
	v_pk_mul_f32 v[4:5], v[0:1], v[4:5]
	v_pk_mul_f32 v[0:1], v[16:17], v[6:7] op_sel_hi:[0,1]
	v_pk_mul_f32 v[6:7], v[10:11], v[0:1]
	v_pk_mul_f32 v[0:1], v[16:17], v[12:13] op_sel_hi:[0,1]
	v_pk_mul_f32 v[10:11], v[2:3], v[0:1]
	v_cvt_pk_f16_f32 v0, v8, v9
	v_cvt_pk_f16_f32 v1, v6, v7
	v_cvt_pk_f16_f32 v2, v4, v5
	v_cvt_pk_f16_f32 v3, v10, v11
	v_add_co_u32_e32 v210, vcc, 0x800, v210
	v_addc_co_u32_e32 v211, vcc, 0, v211, vcc
	flat_store_dwordx4 v[210:211], v[0:3]
	s_andn2_b64 vcc, exec, s[4:5]
	s_mov_b64 s[4:5], -1
	s_cbranch_vccnz .LBB0_566
	s_andn2_b64 vcc, exec, s[0:1]
	s_cbranch_vccnz .LBB0_565
	s_barrier
	s_branch .LBB0_565
